# MLA fast path: waves 4-7 issue their LDS-DMA block between S0 and S1 chains instead of at tile top (de-sync DMA issue within a SIMD)
# baseline (speedup 1.0000x reference)
.Lmla_fast_havek:
	s_mov_b32 s42, 0
	s_andn2_b64 vcc, exec, s[38:39]
	s_cbranch_vccnz .Lmla_fast_nodma
	s_cmp_lt_u32 s5, 0x1000
	s_cbranch_scc0 .Lmla_fast_nodma
	s_add_i32 s34, s30, 2
	s_cmp_gt_u32 s34, s14
	s_cbranch_scc1 .Lmla_fast_d2
	s_and_b32 s8, s34, 2
	s_mulk_i32 s8, 0x6400
	s_add_i32 s34, s8, 0
	s_add_i32 s8, s34, s5
	s_mov_b32 m0, s8
	s_and_b64 vcc, exec, s[36:37]
	global_load_lds_dwordx4 v66, s[26:27]
	s_add_i32 m0, s8, 0x2000
	v_add_u32_e32 v66, v66, v134
	global_load_lds_dwordx4 v68, s[26:27]
	s_add_i32 m0, s8, 0x4000
	v_add_u32_e32 v68, v68, v136
	global_load_lds_dwordx4 v70, s[26:27]
	v_add_u32_e32 v70, v70, v138
	s_cbranch_vccnz .Lmla_fast_d2
	s_add_i32 m0, s34, 0x6000
	s_nop 0
	global_load_lds_dwordx4 v72, s[26:27]
	v_add_u32_e32 v72, v72, v140

.Lmla_fast_nodma:
	s_waitcnt lgkmcnt(0)
	v_mfma_f32_32x32x16_bf16 v[50:65], v[194:197], v[74:77], v[234:249]
	ds_read_b128 v[194:197], v0 offset:6656
	v_add_f32_e32 v254, v202, v203
	v_add_f32_e32 v255, v204, v205
	v_add_f32_e32 v254, v254, v206
	v_add_f32_e32 v255, v255, v207
	v_add_f32_e32 v254, v254, v208
	v_add_f32_e32 v255, v255, v209
	v_mfma_f32_32x32x16_bf16 v[50:65], v[150:153], v[78:81], v[50:65]
	ds_read_b128 v[150:153], v0 offset:6688
	v_add_f32_e32 v254, v254, v210
	v_add_f32_e32 v255, v255, v211
	v_add_f32_e32 v254, v254, v212
	v_add_f32_e32 v255, v255, v213
	v_add_f32_e32 v254, v254, v214
	v_add_f32_e32 v255, v255, v215
	v_mfma_f32_32x32x16_bf16 v[50:65], v[158:161], v[82:85], v[50:65]
	ds_read_b128 v[158:161], v0 offset:6720
	v_add_f32_e32 v254, v254, v216
	v_add_f32_e32 v255, v255, v217
	v_add_f32_e32 v254, v254, v218
	v_add_f32_e32 v255, v255, v219
	v_add_f32_e32 v254, v254, v220
	v_mfma_f32_32x32x16_bf16 v[50:65], v[162:165], v[86:89], v[50:65]
	ds_read_b128 v[162:165], v0 offset:6752
	v_add_f32_e32 v255, v255, v221
	v_add_f32_e32 v254, v254, v222
	v_add_f32_e32 v255, v255, v223
	v_add_f32_e32 v254, v254, v224
	v_add_f32_e32 v255, v255, v225
	v_mfma_f32_32x32x16_bf16 v[50:65], v[174:177], v[90:93], v[50:65]
	ds_read_b128 v[174:177], v0 offset:6784
	v_add_f32_e32 v254, v254, v226
	v_add_f32_e32 v255, v255, v227
	v_add_f32_e32 v254, v254, v228
	v_add_f32_e32 v255, v255, v229
	v_add_f32_e32 v254, v254, v230
	v_mfma_f32_32x32x16_bf16 v[50:65], v[178:181], v[94:97], v[50:65]
	ds_read_b128 v[178:181], v0 offset:6816
	v_add_f32_e32 v255, v255, v231
	v_add_f32_e32 v254, v254, v232
	v_add_f32_e32 v255, v255, v233
	v_add_f32_e32 v254, v254, v255
	v_add_f32_e32 v147, v147, v254
	s_andn2_b64 vcc, exec, s[38:39]
	s_cbranch_vccnz .Lmla_fast_nodma_b
	s_cmp_lt_u32 s5, 0x1000
	s_cbranch_scc1 .Lmla_fast_nodma_b
	s_add_i32 s34, s30, 2
	s_cmp_gt_u32 s34, s14
	s_cbranch_scc1 .Lmla_fast_d2_b
	s_and_b32 s8, s34, 2
	s_mulk_i32 s8, 0x6400
	s_add_i32 s34, s8, 0
	s_add_i32 s8, s34, s5
	s_mov_b32 m0, s8
	s_and_b64 vcc, exec, s[36:37]
	global_load_lds_dwordx4 v66, s[26:27]
	s_add_i32 m0, s8, 0x2000
	v_add_u32_e32 v66, v66, v134
	global_load_lds_dwordx4 v68, s[26:27]
	s_add_i32 m0, s8, 0x4000
	v_add_u32_e32 v68, v68, v136
	global_load_lds_dwordx4 v70, s[26:27]
	v_add_u32_e32 v70, v70, v138
	s_cbranch_vccnz .Lmla_fast_d2_b
	s_add_i32 m0, s34, 0x6000
	s_nop 0
	global_load_lds_dwordx4 v72, s[26:27]
	v_add_u32_e32 v72, v72, v140

.Lmla_fast_nodma_b:
	s_waitcnt lgkmcnt(5)
	v_mfma_f32_32x32x16_bf16 v[34:49], v[194:197], v[74:77], v[234:249]
	ds_read_b64_tr_b16 v[126:127], v142 offset:13312
	ds_read_b64_tr_b16 v[128:129], v142 offset:14848
	ds_read_b64_tr_b16 v[124:125], v142 offset:14912
	ds_read_b64_tr_b16 v[122:123], v142 offset:13376
	s_waitcnt lgkmcnt(8)
	v_mfma_f32_32x32x16_bf16 v[34:49], v[150:153], v[78:81], v[34:49]
	ds_read_b64_tr_b16 v[118:119], v142 offset:16384
	ds_read_b64_tr_b16 v[120:121], v142 offset:17920
	ds_read_b64_tr_b16 v[116:117], v142 offset:17984
	ds_read_b64_tr_b16 v[114:115], v142 offset:16448
	s_waitcnt lgkmcnt(11)
	v_mfma_f32_32x32x16_bf16 v[34:49], v[158:161], v[82:85], v[34:49]
	ds_read_b64_tr_b16 v[110:111], v142 offset:19456
	ds_read_b64_tr_b16 v[112:113], v142 offset:20992
	ds_read_b64_tr_b16 v[108:109], v142 offset:21056
	ds_read_b64_tr_b16 v[106:107], v142 offset:19520
	v_max3_f32 v0, v50, v51, v52
	v_max3_f32 v0, v0, v53, v54
	s_waitcnt lgkmcnt(11)
	v_mfma_f32_32x32x16_bf16 v[34:49], v[162:165], v[86:89], v[34:49]
	ds_read_b64_tr_b16 v[102:103], v142 offset:22528
	ds_read_b64_tr_b16 v[104:105], v142 offset:24064
	ds_read_b64_tr_b16 v[100:101], v142 offset:24128
	ds_read_b64_tr_b16 v[98:99], v142 offset:22592
	v_max3_f32 v0, v0, v55, v56
	v_max3_f32 v0, v0, v57, v58
	v_mfma_f32_32x32x16_bf16 v[34:49], v[174:177], v[90:93], v[34:49]
	v_max3_f32 v0, v0, v59, v60
	v_max3_f32 v0, v0, v61, v62
	v_max3_f32 v0, v0, v63, v64
	v_max3_f32 v0, v0, v65, v65
	v_exp_f32_e32 v202, v50
	v_mfma_f32_32x32x16_bf16 v[34:49], v[178:181], v[94:97], v[34:49]
	s_and_b64 vcc, exec, s[16:17]
	s_cbranch_vccz .Lmla_fast_nostag
	s_waitcnt vmcnt(0) lgkmcnt(0)
	s_barrier
	s_mov_b64 s[16:17], 0
